# residual GEMMs: half of the CUs run their split-K slice before the whole unit, so epilogue HBM bursts are de-synchronised
# baseline (speedup 1.0000x reference)
.LBB0_323:
	s_and_b64 s[6:7], s[0:1], exec
	s_cselect_b32 s5, 32, 36
	s_lshr_b32 s34, s3, 7
	s_and_b64 s[0:1], s[0:1], exec
	s_mul_i32 s8, s35, s5
	s_cselect_b32 s0, 0x100, 0
	s_add_i32 s6, s8, s0
	v_readlane_b32 s10, v246, 59
	v_readlane_b32 s11, v246, 60
	s_cmp_lt_i32 s10, s6
	s_cselect_b64 s[10:11], -1, 0
	s_mov_b64 s[0:1], 0
	s_and_b64 vcc, exec, s[10:11]
	s_cbranch_vccz .LBB0_328
	v_readlane_b32 s0, v246, 59
	v_readlane_b32 s1, v246, 60
	s_lshl_b32 s100, s36, 1
	s_cmp_eq_u32 s6, s100
	s_cbranch_scc0 .Lsw0_no
	s_cmp_eq_u32 s8, s36
	s_cbranch_scc0 .Lsw0_no
	s_and_b32 s100, s0, 32
	s_cmp_lg_u32 s100, 0
	s_cbranch_scc0 .Lsw0_no
	s_mov_b64 s[14:15], -1
	s_branch .Lsw0_tail
.Lsw0_no:
	s_cmp_lt_i32 s0, s8
	s_mov_b64 s[14:15], -1
	s_cbranch_scc1 .LBB0_326
	v_readlane_b32 s0, v246, 59
	s_sub_i32 s0, s0, s8
.Lsw0_tail:
	s_lshr_b32 s2, s0, 5
	s_bfe_u32 s0, s0, 0x20003
	s_or_b32 s54, s0, 32
	s_lshr_b32 s7, s3, 10
	s_and_b32 s14, s34, 4
	v_readlane_b32 s1, v246, 60
	s_cmp_lt_u32 s2, s14
	s_mul_i32 s15, s2, s7
	s_cselect_b64 s[0:1], -1, 0
	s_min_u32 s14, s2, s14
	s_add_i32 s88, s15, s14
	s_cmp_lg_u64 s[0:1], 0
	s_addc_u32 s0, s7, 0
	s_lshl_b32 s55, s0, 1
	s_lshl_b64 s[0:1], s[88:89], 8
	s_mov_b64 s[14:15], 0
	s_mov_b32 s88, s2

.LBB0_334:
	s_add_i32 s80, s80, 1
	s_mov_b32 s100, s80
	s_lshl_b32 s101, s36, 1
	s_cmp_eq_u32 s6, s101
	s_cbranch_scc0 .Lsw1_no
	s_cmp_eq_u32 s8, s36
	s_cbranch_scc0 .Lsw1_no
	v_readlane_b32 s101, v246, 59
	s_nop 0
	s_and_b32 s101, s101, 32
	s_cmp_lg_u32 s101, 0
	s_cbranch_scc0 .Lsw1_no
	s_cmp_lt_u32 s80, 2
	s_cbranch_scc0 .Lsw1_no
	s_xor_b32 s100, s80, 1
.Lsw1_no:
	s_mul_i32 s0, s100, s37
	s_mul_hi_u32 s1, s100, s36
	s_add_i32 s1, s1, s0
	s_mul_i32 s0, s100, s36
	v_readlane_b32 s46, v246, 59
	v_readlane_b32 s47, v246, 60
	s_add_u32 s46, s0, s46
	s_addc_u32 s47, s1, s47
	v_mov_b64_e32 v[2:3], s[6:7]
	v_cmp_ge_i64_e32 vcc, s[46:47], v[2:3]
	v_cmp_lt_i64_e64 s[0:1], s[46:47], v[2:3]
	s_cbranch_vccnz .LBB0_339
	v_mov_b64_e32 v[2:3], s[8:9]
	v_cmp_lt_i64_e32 vcc, s[46:47], v[2:3]
	s_mov_b64 s[52:53], -1
	s_and_b64 vcc, exec, vcc
	s_cbranch_vccnz .LBB0_337
	s_sub_i32 s14, s46, s8
	s_ashr_i32 s81, s14, 5
	s_bfe_u32 s14, s14, 0x20003
	s_or_b32 s40, s14, 32
	s_and_b32 s91, s46, 7
	s_cmp_lt_i32 s81, s34
	s_mul_i32 s14, s81, s3
	s_cselect_b64 s[52:53], -1, 0
	s_min_i32 s15, s81, s34
	s_add_i32 s14, s14, s15
	s_cmp_lg_u64 s[52:53], 0
	s_addc_u32 s15, s3, 0
	s_lshl_b32 s41, s15, 1
	s_mov_b64 s[52:53], 0
